# QKV GEMM: custom tile order (per XCD half the WGs start with light Q tile, half with heavy K/V tile) so epilogue store bursts overlap other WGs mainloops
# speedup vs baseline: 1.0131x; 1.0077x over previous
.LBB0_203:
	s_or_b64 exec, exec, s[0:1]
	s_add_u32 s8, s28, 0x6248000
	s_addc_u32 s9, s29, 0
	s_lshl_b32 s10, s30, 3
	s_lshl_b32 s60, s16, 3
	s_add_u32 s87, s26, 0x2000000
	s_addc_u32 s95, s27, 0
	s_add_u32 s12, s28, 0x7648000
	s_addc_u32 s13, s29, 0
	s_add_u32 s96, s28, 0xee48200
	s_addc_u32 s97, s29, 0
	s_add_u32 s64, s28, 0xee48400
	s_addc_u32 s65, s29, 0
	s_add_u32 s90, s28, 0xee48500
	s_addc_u32 s91, s29, 0
	s_add_u32 s40, s28, 0xee48600
	s_addc_u32 s41, s29, 0
	s_add_u32 s42, s28, 0xee48700
	s_addc_u32 s43, s29, 0
	s_add_u32 s58, s28, 0xee48800
	s_addc_u32 s59, s29, 0
	s_add_u32 s0, s28, 0xee48900
	s_addc_u32 s1, s29, 0
	v_writelane_b32 v252, s0, 48
	s_mov_b32 s15, 0
	s_mov_b32 s14, s16
	v_writelane_b32 v252, s1, 49
	s_add_u32 s0, s28, 0xee48a00
	s_addc_u32 s1, s29, 0
	v_writelane_b32 v252, s0, 50
	s_waitcnt lgkmcnt(0)
	v_mbcnt_lo_u32_b32 v0, -1, 0
	v_writelane_b32 v255, s90, 0
	v_writelane_b32 v252, s1, 51
	s_add_u32 s0, s28, 0xee48b00
	s_addc_u32 s1, s29, 0
	v_writelane_b32 v252, s0, 52
	v_writelane_b32 v255, s91, 1
	v_writelane_b32 v255, s40, 2
	v_writelane_b32 v252, s1, 53
	s_add_u32 s0, s28, 0xee48c00
	s_addc_u32 s1, s29, 0
	v_writelane_b32 v252, s0, 54
	v_writelane_b32 v255, s41, 3
	v_writelane_b32 v255, s42, 4
	v_writelane_b32 v252, s1, 55
	s_add_u32 s0, s28, 0xee48d00
	s_addc_u32 s1, s29, 0
	v_writelane_b32 v252, s0, 56
	v_mbcnt_hi_u32_b32 v198, -1, v0
	v_writelane_b32 v255, s43, 5
	v_writelane_b32 v252, s1, 57
	s_add_u32 s0, s28, 0xee48e00
	s_addc_u32 s1, s29, 0
	v_writelane_b32 v252, s0, 58
	s_mul_i32 s31, s31, s30
	v_and_b32_e32 v0, 64, v198
	v_writelane_b32 v252, s1, 59
	s_add_u32 s0, s28, 0xee48f00
	s_addc_u32 s1, s29, 0
	v_writelane_b32 v252, s0, 60
	v_writelane_b32 v255, s58, 6
	s_mul_i32 s31, s31, s94
	v_writelane_b32 v252, s1, 61
	s_add_u32 s0, s28, 0xee49000
	s_addc_u32 s1, s29, 0
	v_writelane_b32 v252, s0, 62
	v_mov_b32_e32 v1, 0
	v_mov_b32_e32 v193, 0x358637bd
	v_writelane_b32 v252, s1, 63
	s_add_u32 s0, s28, 0xee49100
	s_addc_u32 s1, s29, 0
	v_writelane_b32 v253, s0, 0
	v_mov_b32_e32 v194, 0x260
	v_mov_b32_e32 v195, 0x1000
	v_writelane_b32 v253, s1, 1
	s_add_u32 s0, s28, 0xee49200
	s_addc_u32 s1, s29, 0
	v_writelane_b32 v253, s0, 2
	v_mov_b32_e32 v196, 0x2000
	v_mov_b32_e32 v197, 1
	v_writelane_b32 v253, s1, 3
	s_add_u32 s0, s28, 0xee49300
	s_addc_u32 s1, s29, 0
	v_writelane_b32 v253, s0, 4
	v_add_u32_e32 v199, 64, v0
	v_xor_b32_e32 v200, 32, v198
	v_writelane_b32 v253, s1, 5
	s_add_u32 s0, s28, 0xee4b400
	s_addc_u32 s1, s29, 0
	v_writelane_b32 v253, s0, 6
	v_xor_b32_e32 v201, 16, v198
	v_xor_b32_e32 v251, 4, v198
	v_writelane_b32 v253, s1, 7
	s_add_u32 s0, s28, 0xee4b500
	s_addc_u32 s1, s29, 0
	v_writelane_b32 v253, s0, 8
	v_xor_b32_e32 v208, 2, v198
	v_xor_b32_e32 v206, 1, v198
	v_writelane_b32 v253, s1, 9
	s_add_u32 s0, s28, 0xee4c000
	s_addc_u32 s1, s29, 0
	v_writelane_b32 v253, s0, 10
	v_mov_b64_e32 v[174:175], 0x9f
	v_mov_b64_e32 v[176:177], 0xa0
	v_writelane_b32 v253, s1, 11
	s_lshl_b32 s0, s16, 4
	s_add_u32 s92, s28, 0x9e48000
	v_writelane_b32 v253, s0, 12
	s_addc_u32 s93, s29, 0
	s_lshl_b64 s[0:1], s[14:15], 9
	v_writelane_b32 v253, s0, 13
	v_mov_b32_e32 v207, 0x7f800000
	s_mov_b32 s88, 0xf149f2ca
	v_writelane_b32 v253, s1, 14
	s_mov_b32 s0, s30
	s_mov_b32 s1, s15
	s_lshl_b64 s[2:3], s[0:1], 9
	v_writelane_b32 v253, s2, 15
	s_movk_i32 s89, 0x1600
	s_mov_b32 s72, 0
	v_writelane_b32 v253, s3, 16
	s_add_u32 s2, s28, 0x1000000
	v_writelane_b32 v253, s2, 17
	s_addc_u32 s2, s29, 0
	s_cmpk_lt_i32 s16, 0x140
	v_writelane_b32 v253, s2, 18
	s_cselect_b64 s[2:3], -1, 0
	v_writelane_b32 v253, s2, 19
	s_ashr_i32 s33, s16, 31
	v_writelane_b32 v255, s59, 7
	v_writelane_b32 v253, s3, 20
	s_lshr_b32 s2, s33, 29
	s_add_i32 s2, s16, s2
	s_ashr_i32 s6, s2, 3
	s_and_b32 s2, s2, -8
	s_sub_i32 s7, s16, s2
	s_cmp_lt_i32 s7, 0
	s_cselect_b32 s2, 41, 40
	s_mul_i32 s2, s2, s7
	s_movk_i32 s3, 0x6f
	s_cselect_b32 s11, 61, 60
	s_cselect_b32 s18, 21, 20
	s_cselect_b32 s19, s3, 0x6e
	s_add_i32 s2, s2, s6
	s_ashr_i32 s3, s2, 31
	s_lshr_b32 s3, s3, 26
	s_add_i32 s3, s2, s3
	s_ashr_i32 s4, s3, 6
	s_and_b32 s3, s3, 0xffc0
	s_sub_i32 s3, s2, s3
	s_bfe_i32 s2, s3, 0x80000
	s_bfe_u32 s2, s2, 0x3000c
	s_add_i32 s5, s3, s2
	s_bfe_i32 s2, s5, 0x80000
	s_and_b32 s5, s5, 0xf8
	s_sub_i32 s3, s3, s5
	s_lshl_b32 s4, s4, 3
	s_sext_i32_i16 s17, s2
	s_sext_i32_i8 s3, s3
	s_add_i32 s20, s4, s3
	s_ashr_i32 s3, s17, 3
	s_lshr_b32 s2, s17, 3
	v_writelane_b32 v253, s3, 21
	s_mov_b32 s4, s20
	v_writelane_b32 v253, s4, 22
	s_bfe_i64 s[2:3], s[2:3], 0x100000
	s_ashr_i32 s21, s20, 31
	v_writelane_b32 v253, s5, 23
	s_lshl_b64 s[2:3], s[2:3], 19
	s_lshl_b64 s[4:5], s[20:21], 19
	v_writelane_b32 v253, s2, 24
	s_barrier
	s_nop 0
	v_writelane_b32 v253, s3, 25
	s_add_u32 s2, s8, s4
	s_addc_u32 s3, s9, s5
	s_add_u32 s4, s2, 0x40000
	v_writelane_b32 v253, s2, 26
	s_addc_u32 s5, s3, 0
	s_ashr_i32 s17, s30, 31
	v_writelane_b32 v253, s3, 27
	s_add_u32 s34, s28, 0x8a48000
	v_writelane_b32 v253, s4, 28
	s_addc_u32 s35, s29, 0
	s_add_u32 s2, s26, 0x2800000
	v_writelane_b32 v253, s5, 29
	v_writelane_b32 v253, s2, 30
	s_addc_u32 s2, s27, 0
	v_writelane_b32 v253, s2, 31
	s_add_u32 s2, s26, 0x6800000
	v_writelane_b32 v253, s2, 32
	s_addc_u32 s2, s27, 0
	v_writelane_b32 v253, s2, 33
	s_cmpk_lt_i32 s16, 0x1e0
	s_mul_i32 s2, s11, s7
	s_cselect_b64 s[4:5], -1, 0
	s_add_i32 s2, s2, s6
	v_writelane_b32 v253, s4, 34
	s_mul_hi_i32 s3, s2, 0x2aaaaaab
	s_nop 0
	v_writelane_b32 v253, s5, 35
	s_lshr_b32 s4, s3, 31
	s_ashr_i32 s3, s3, 4
	s_add_i32 s3, s3, s4
	s_mul_i32 s4, s3, 0x60
	s_sub_i32 s2, s2, s4
	s_bfe_i32 s4, s2, 0x80000
	s_bfe_u32 s4, s4, 0x3000c
	s_add_i32 s4, s2, s4
	s_and_b32 s5, s4, 0xf8
	s_sub_i32 s2, s2, s5
	s_bfe_i32 s4, s4, 0x80000
	s_lshl_b32 s3, s3, 3
	s_sext_i32_i16 s4, s4
	s_sext_i32_i8 s2, s2
	s_add_i32 s20, s3, s2
	s_cmpk_lg_i32 s30, 0x100
	s_cbranch_scc1 .Lqkv_map0_done
	s_cmpk_lt_i32 s6, 16
	s_cselect_b32 s98, 0, 16
	s_cselect_b32 s99, 0, 4
	s_sub_i32 s98, s6, s98
	s_mul_i32 s4, s98, 13
	s_lshr_b32 s4, s4, 6
	s_mul_i32 s20, s4, 5
	s_sub_i32 s98, s98, s20
	s_mul_i32 s20, s7, 5
	s_add_i32 s20, s20, s98
	s_add_i32 s4, s4, s99
	s_lshl_b32 s4, s4, 3
.Lqkv_map0_done:
	s_ashr_i32 s2, s4, 3
	v_writelane_b32 v253, s2, 36
	s_lshr_b32 s2, s4, 3
	s_add_u32 s4, s28, 0x5a48000
	s_addc_u32 s5, s29, 0
	v_writelane_b32 v253, s4, 37
	s_mul_i32 s3, s18, s7
	s_nop 0
	v_writelane_b32 v253, s5, 38
	s_add_u32 s4, s28, 0x5e48000
	s_addc_u32 s5, s29, 0
	s_add_u32 s22, s28, 0xb248000
	s_addc_u32 s23, s29, 0
	v_writelane_b32 v253, s4, 39
	s_cmpk_lt_i32 s16, 0x500
	s_nop 0
	v_writelane_b32 v253, s5, 40
	s_cselect_b64 s[4:5], -1, 0
	v_writelane_b32 v253, s4, 41
	s_nop 1
	v_writelane_b32 v253, s5, 42
	s_add_u32 s4, s28, 0xc00000
	s_addc_u32 s5, s29, 0
	s_cmpk_lt_i32 s16, 0xa0
	v_writelane_b32 v253, s4, 43
	s_cselect_b64 s[52:53], -1, 0
	s_add_i32 s3, s3, s6
	v_writelane_b32 v253, s5, 44
	s_ashr_i32 s4, s3, 31
	s_lshr_b32 s4, s4, 27
	s_add_i32 s4, s3, s4
	s_and_b32 s5, s4, 0xffe0
	s_sub_i32 s3, s3, s5
	s_bfe_i32 s5, s3, 0x80000
	s_bfe_u32 s5, s5, 0x3000c
	s_add_i32 s5, s3, s5
	s_and_b32 s11, s5, 0xf8
	s_sub_i32 s3, s3, s11
	s_ashr_i32 s4, s4, 5
	s_bfe_i32 s5, s5, 0x80000
	s_lshl_b32 s4, s4, 3
	s_sext_i32_i16 s5, s5
	s_sext_i32_i8 s3, s3
	s_add_i32 s54, s4, s3
	s_lshr_b32 s4, s5, 3
	s_ashr_i32 s3, s5, 3
	s_bfe_i64 s[4:5], s[4:5], 0x100000
	v_writelane_b32 v253, s3, 45
	s_lshl_b64 s[4:5], s[4:5], 19
	s_ashr_i32 s55, s54, 31
	v_writelane_b32 v253, s4, 46
	s_mul_i32 s3, s19, s7
	s_nop 0
	v_writelane_b32 v253, s5, 47
	s_lshl_b64 s[4:5], s[54:55], 19
	s_add_u32 s4, s22, s4
	v_writelane_b32 v253, s22, 48
	s_addc_u32 s5, s23, s5
	s_add_u32 s18, s4, 0x40000
	v_writelane_b32 v253, s23, 49
	v_writelane_b32 v253, s4, 50
	s_addc_u32 s19, s5, 0
	s_nop 0
	v_writelane_b32 v253, s5, 51
	v_writelane_b32 v253, s18, 52
	s_add_i32 s4, s30, 0xffffff60
	s_nop 0
	v_writelane_b32 v253, s19, 53
	v_writelane_b32 v253, s4, 54
	s_or_b64 s[4:5], s[52:53], s[56:57]
	v_writelane_b32 v253, s4, 55
	s_cmpk_lt_u32 s16, 0x2b0
	s_nop 0
	v_writelane_b32 v253, s5, 56
	s_cselect_b64 s[4:5], -1, 0
	v_writelane_b32 v253, s4, 57
	s_nop 1
	v_writelane_b32 v253, s5, 58
	s_add_i32 s4, s16, 0x60
	v_writelane_b32 v253, s4, 59
	s_add_u32 s4, s28, 0x4400000
	s_addc_u32 s5, s29, 0
	v_writelane_b32 v253, s4, 60
	s_nop 1
	v_writelane_b32 v253, s5, 61
	s_add_u32 s4, s28, 0x1800000
	s_addc_u32 s5, s29, 0
	v_writelane_b32 v253, s4, 62
	s_cmpk_lt_i32 s16, 0x370
	s_nop 0
	v_writelane_b32 v253, s5, 63
	s_cselect_b64 s[4:5], -1, 0
	v_writelane_b32 v254, s4, 0
	s_add_i32 s3, s3, s6
	s_nop 0
	v_writelane_b32 v254, s5, 1
	s_mul_hi_i32 s4, s3, 0x2e8ba2e9
	s_lshr_b32 s5, s4, 31
	s_ashr_i32 s4, s4, 5
	s_add_i32 s4, s4, s5
	s_mul_i32 s5, s4, 0xb0
	s_sub_i32 s3, s3, s5
	s_bfe_u32 s5, s3, 0x3001c
	s_add_i32 s5, s3, s5
	s_and_b32 s6, s5, 0xfff8
	s_sub_i32 s3, s3, s6
	s_lshl_b32 s4, s4, 3
	s_sext_i32_i16 s5, s5
	s_sext_i32_i16 s3, s3
	s_add_i32 s6, s4, s3
	s_lshr_b32 s4, s5, 3
	s_ashr_i32 s3, s5, 3
	s_bfe_i64 s[4:5], s[4:5], 0x100000
	v_writelane_b32 v254, s3, 2
	s_lshl_b64 s[4:5], s[4:5], 19
	v_writelane_b32 v254, s4, 3
	s_ashr_i32 s7, s6, 31
	s_mul_hi_i32 s3, s54, 0x160000
	v_writelane_b32 v254, s5, 4
	s_mov_b32 s4, s6
	v_writelane_b32 v254, s4, 5
	s_nop 1
	v_writelane_b32 v254, s5, 6
	s_lshl_b64 s[4:5], s[6:7], 19
	s_add_u32 s4, s8, s4
	s_addc_u32 s5, s9, s5
	s_add_u32 s6, s4, 0x40000
	v_writelane_b32 v254, s4, 7
	s_addc_u32 s7, s5, 0
	s_cmpk_lt_i32 s16, 0x70
	v_writelane_b32 v254, s5, 8
	v_writelane_b32 v254, s6, 9
	s_cselect_b64 s[4:5], -1, 0
	s_or_b64 s[4:5], s[4:5], s[56:57]
	v_writelane_b32 v254, s7, 10
	v_writelane_b32 v254, s4, 11
	s_add_i32 s6, s16, 0xffffff90
	s_cmpk_lt_u32 s6, 0x60
	v_writelane_b32 v254, s5, 12
	s_mov_b32 s4, s54
	v_writelane_b32 v254, s4, 13
	s_cselect_b64 s[18:19], -1, 0
	s_nop 0
	v_writelane_b32 v254, s5, 14
	s_mul_i32 s4, s54, 0x160000
	v_writelane_b32 v254, s18, 15
	s_add_u32 s4, s12, s4
	s_addc_u32 s5, s13, s3
	v_writelane_b32 v254, s19, 16
	s_add_u32 s18, s4, 0xb0000
	v_writelane_b32 v254, s4, 17
	s_addc_u32 s19, s5, 0
	s_cmpk_lt_i32 s30, 0xa1
	v_writelane_b32 v254, s5, 18
	v_writelane_b32 v254, s18, 19
	s_cselect_b64 s[4:5], -1, 0
	s_bfe_i64 s[2:3], s[2:3], 0x100000
	v_writelane_b32 v254, s19, 20
	v_writelane_b32 v254, s52, 21
	s_or_b64 s[4:5], s[52:53], s[4:5]
	s_lshl_b64 s[2:3], s[2:3], 19
	v_writelane_b32 v254, s53, 22
	v_writelane_b32 v254, s4, 23
	s_ashr_i32 s21, s20, 31
	s_nop 0
	v_writelane_b32 v254, s5, 24
	v_writelane_b32 v254, s2, 25
	s_nop 1
	v_writelane_b32 v254, s3, 26
	s_add_i32 s2, s16, 0xffffff60
	v_writelane_b32 v254, s2, 27
	s_mov_b32 s2, s20
	v_writelane_b32 v254, s2, 28
	s_nop 1
	v_writelane_b32 v254, s3, 29
	s_lshl_b64 s[2:3], s[20:21], 19
	s_add_u32 s2, s8, s2
	s_addc_u32 s3, s9, s3
	s_add_u32 s4, s2, 0x40000
	v_writelane_b32 v254, s2, 30
	s_addc_u32 s5, s3, 0
	s_ashr_i32 s11, s10, 31
	v_writelane_b32 v254, s3, 31
	v_writelane_b32 v254, s4, 32
	s_add_i32 s2, s60, s10
	s_nop 0
	v_writelane_b32 v254, s5, 33
	v_writelane_b32 v254, s60, 34
	v_writelane_b32 v254, s2, 35
	s_lshl_b64 s[2:3], s[10:11], 11
	v_writelane_b32 v254, s2, 36
	s_lshl_b32 s4, s6, 6
	s_mov_b32 s5, s15
	v_writelane_b32 v254, s3, 37
	s_lshl_b64 s[2:3], s[10:11], 12
	v_writelane_b32 v254, s2, 38
	s_mov_b64 s[60:61], 0x80
	s_nop 0
	v_writelane_b32 v254, s3, 39
	s_lshl_b64 s[2:3], s[14:15], 12
	s_add_u32 s2, s28, s2
	s_addc_u32 s3, s29, s3
	s_add_u32 s2, s2, 0x9e48000
	s_addc_u32 s3, s3, 0
	v_writelane_b32 v254, s2, 40
	s_lshl_b64 s[0:1], s[0:1], 12
	s_nop 0
	v_writelane_b32 v254, s3, 41
	v_writelane_b32 v254, s4, 42
	s_nop 1
	v_writelane_b32 v254, s5, 43
	v_writelane_b32 v254, s0, 44
	s_nop 1
	v_writelane_b32 v254, s1, 45
	s_lshl_b32 s0, s16, 1
	s_addk_i32 s0, 0xc0
	v_writelane_b32 v254, s0, 46
	s_lshl_b32 s0, s30, 1
	s_addk_i32 s0, 0xfec0
	v_writelane_b32 v254, s0, 47
	s_lshl_b32 s0, s30, 4
	s_addk_i32 s0, 0xf600
	v_writelane_b32 v254, s0, 48
	s_lshl_b32 s0, s30, 8
	s_add_i32 s0, s0, 0xffff6000
	v_writelane_b32 v254, s0, 49
	s_add_i32 s0, 0, 0x24000
	v_writelane_b32 v254, s0, 50
	s_add_i32 s0, 0, 0x24004
	v_writelane_b32 v254, s0, 51
	s_add_i32 s0, 0, 0x9000
	v_writelane_b32 v254, s0, 52
	s_mov_b32 s1, 0xbf738138
	v_writelane_b32 v254, s0, 53
	s_nop 1
	v_writelane_b32 v254, s1, 54
	s_mov_b32 s1, 0xbfa11111
	v_writelane_b32 v254, s0, 55
	s_nop 1
	v_writelane_b32 v254, s1, 56
	s_mov_b32 s1, 0xbfc55555
	v_writelane_b32 v254, s0, 57
	s_nop 1
	v_writelane_b32 v254, s1, 58
	v_writelane_b32 v254, s95, 59
	v_writelane_b32 v254, s96, 60
	s_nop 1
	v_writelane_b32 v254, s97, 61
	v_writelane_b32 v254, s64, 62
	s_nop 1
	v_writelane_b32 v254, s65, 63
	s_branch .LBB0_206

.LBB0_487:
	s_add_i32 s97, s97, 1
	s_mul_i32 s2, s97, s17
	s_mul_hi_u32 s3, s97, s30
	s_add_i32 s3, s3, s2
	s_mul_i32 s2, s97, s30
	s_add_u32 s58, s2, s16
	s_addc_u32 s59, s3, s33
	v_mov_b64_e32 v[2:3], 0x1df
	v_cmp_gt_i64_e64 s[2:3], s[58:59], v[2:3]
	s_and_b64 vcc, exec, s[2:3]
	s_cbranch_vccnz .LBB0_489
	s_cmpk_lg_i32 s30, 0x100
	s_cbranch_scc1 .Lqkv_map1_orig
	s_and_b32 s18, s16, 7
	s_lshr_b32 s19, s16, 3
	s_cmpk_lt_i32 s19, 16
	s_cbranch_scc0 .Lqkv_map1_b
	s_add_i32 s22, s19, 16
	s_mov_b32 s23, 4
	s_branch .Lqkv_map1_c
.Lqkv_map1_b:
	s_cmpk_lt_i32 s19, 20
	s_cbranch_scc0 .Lqkv_map1_d
	s_mov_b32 s22, s19
	s_mov_b32 s23, 0
	s_branch .Lqkv_map1_c
.Lqkv_map1_d:
	s_add_i32 s22, s19, 12
	s_mov_b32 s23, 4
.Lqkv_map1_c:
	s_mul_i32 s54, s22, 13
	s_lshr_b32 s54, s54, 6
	s_mul_i32 s19, s54, 5
	s_sub_i32 s22, s22, s19
	s_mul_i32 s18, s18, 5
	s_add_i32 s18, s18, s22
	s_add_i32 s54, s54, s23
	s_branch .LBB0_489
.Lqkv_map1_orig:
	s_ashr_i32 s18, s58, 31
	s_lshr_b32 s18, s18, 29
	s_add_i32 s18, s58, s18
	s_ashr_i32 s19, s18, 3
	s_and_b32 s18, s18, -8
	s_sub_i32 s18, s58, s18
	s_cmp_lt_i32 s18, 0
	s_cselect_b32 s22, 61, 60
	s_mul_i32 s18, s22, s18
	s_add_i32 s18, s18, s19
	s_mul_hi_i32 s19, s18, 0x2aaaaaab
	s_lshr_b32 s22, s19, 31
	s_ashr_i32 s19, s19, 4
	s_add_i32 s19, s19, s22
	s_lshl_b32 s22, s19, 3
	s_sub_i32 s23, 40, s22
	s_min_i32 s23, s23, 8
	s_abs_i32 s54, s23
	v_cvt_f32_u32_e32 v0, s54
	s_sub_i32 s62, 0, s54
	s_mulk_i32 s19, 0x60
	s_sub_i32 s18, s18, s19
	v_rcp_iflag_f32_e32 v0, v0
	s_abs_i32 s19, s18
	s_xor_b32 s55, s18, s23
	s_ashr_i32 s55, s55, 31
	v_mul_f32_e32 v0, 0x4f7ffffe, v0
	v_cvt_u32_f32_e32 v0, v0
	s_nop 0
	v_readfirstlane_b32 s63, v0
	s_mul_i32 s62, s62, s63
	s_mul_hi_u32 s62, s63, s62
	s_add_i32 s63, s63, s62
	s_mul_hi_u32 s62, s19, s63
	s_mul_i32 s63, s62, s54
	s_sub_i32 s19, s19, s63
	s_add_i32 s67, s62, 1
	s_sub_i32 s63, s19, s54
	s_cmp_ge_u32 s19, s54
	s_cselect_b32 s62, s67, s62
	s_cselect_b32 s19, s63, s19
	s_add_i32 s63, s62, 1
	s_cmp_ge_u32 s19, s54
	s_cselect_b32 s19, s63, s62
	s_xor_b32 s19, s19, s55
	s_sub_i32 s54, s19, s55
	s_mul_i32 s19, s54, s23
	s_sub_i32 s18, s18, s19
	s_add_i32 s18, s18, s22

	.amdhsa_kernel _Z11mega_kernel6Params
		.amdhsa_group_segment_fixed_size 0
		.amdhsa_private_segment_fixed_size 0
		.amdhsa_kernarg_size 504
		.amdhsa_user_sgpr_count 2
		.amdhsa_user_sgpr_dispatch_ptr 0
		.amdhsa_user_sgpr_queue_ptr 0
		.amdhsa_user_sgpr_kernarg_segment_ptr 1
		.amdhsa_user_sgpr_dispatch_id 0
		.amdhsa_user_sgpr_kernarg_preload_length 0
		.amdhsa_user_sgpr_kernarg_preload_offset 0
		.amdhsa_user_sgpr_private_segment_size 0
		.amdhsa_uses_dynamic_stack 0
		.amdhsa_enable_private_segment 0
		.amdhsa_system_sgpr_workgroup_id_x 1
		.amdhsa_system_sgpr_workgroup_id_y 0
		.amdhsa_system_sgpr_workgroup_id_z 0
		.amdhsa_system_sgpr_workgroup_info 0
		.amdhsa_system_vgpr_workitem_id 2
		.amdhsa_next_free_vgpr 256
		.amdhsa_next_free_sgpr 100
		.amdhsa_accum_offset 256
		.amdhsa_reserve_vcc 1
		.amdhsa_float_round_mode_32 0
		.amdhsa_float_round_mode_16_64 0
		.amdhsa_float_denorm_mode_32 3
		.amdhsa_float_denorm_mode_16_64 3
		.amdhsa_dx10_clamp 1
		.amdhsa_ieee_mode 1
		.amdhsa_fp16_overflow 0
		.amdhsa_tg_split 0
		.amdhsa_exception_fp_ieee_invalid_op 0
		.amdhsa_exception_fp_denorm_src 0
		.amdhsa_exception_fp_ieee_div_zero 0
		.amdhsa_exception_fp_ieee_overflow 0
		.amdhsa_exception_fp_ieee_underflow 0
		.amdhsa_exception_fp_ieee_inexact 0
		.amdhsa_exception_int_div_zero 0
	.end_amdhsa_kernel

amdhsa.kernels:
  - .agpr_count:     0
    .args:
      - .offset:         0
        .size:           248
        .value_kind:     by_value
      - .offset:         248
        .size:           4
        .value_kind:     hidden_block_count_x
      - .offset:         252
        .size:           4
        .value_kind:     hidden_block_count_y
      - .offset:         256
        .size:           4
        .value_kind:     hidden_block_count_z
      - .offset:         260
        .size:           2
        .value_kind:     hidden_group_size_x
      - .offset:         262
        .size:           2
        .value_kind:     hidden_group_size_y
      - .offset:         264
        .size:           2
        .value_kind:     hidden_group_size_z
      - .offset:         266
        .size:           2
        .value_kind:     hidden_remainder_x
      - .offset:         268
        .size:           2
        .value_kind:     hidden_remainder_y
      - .offset:         270
        .size:           2
        .value_kind:     hidden_remainder_z
      - .offset:         288
        .size:           8
        .value_kind:     hidden_global_offset_x
      - .offset:         296
        .size:           8
        .value_kind:     hidden_global_offset_y
      - .offset:         304
        .size:           8
        .value_kind:     hidden_global_offset_z
      - .offset:         312
        .size:           2
        .value_kind:     hidden_grid_dims
      - .offset:         336
        .size:           8
        .value_kind:     hidden_multigrid_sync_arg
      - .offset:         368
        .size:           4
        .value_kind:     hidden_dynamic_lds_size
    .group_segment_fixed_size: 0
    .kernarg_segment_align: 8
    .kernarg_segment_size: 504
    .language:       OpenCL C
    .language_version:
      - 2
      - 0
    .max_flat_workgroup_size: 512
    .name:           _Z11mega_kernel6Params
    .private_segment_fixed_size: 0
    .sgpr_count:     106
    .sgpr_spill_count: 217
    .symbol:         _Z11mega_kernel6Params.kd
    .uniform_work_group_size: 1
    .uses_dynamic_stack: false
    .vgpr_count:     256
    .vgpr_spill_count: 0
    .wavefront_size: 64
